# ret task: state_ret loads issued together with the V staging loads (one round trip fewer)
# speedup vs baseline: 1.0029x; 1.0002x over previous
.LBB0_298:
	s_and_b32 s57, s53, 3
	s_cmp_lg_u32 s38, 0
	s_cselect_b64 s[2:3], -1, 0
	s_cmp_eq_u32 s38, 0
	s_mul_i32 s40, s55, 0x1600
	s_cselect_b64 s[0:1], -1, 0
	s_mul_hi_i32 s39, s55, 0x1600
	s_add_u32 s40, s20, s40
	v_mov_b32_e32 v18, v229
	s_addc_u32 s39, s21, s39
	s_lshl_b32 s41, s57, 7
	s_add_u32 s40, s40, s41
	s_waitcnt lgkmcnt(0)
	v_lshlrev_b32_e32 v1, 2, v18
	v_and_b32_e32 v19, 60, v1
	s_addc_u32 s41, s39, 0
	v_lshlrev_b32_e32 v200, 1, v19
	v_lshl_add_u64 v[2:3], s[40:41], 0, v[200:201]
	s_mov_b64 s[40:41], 0x1200
	v_lshl_add_u64 v[2:3], v[2:3], 0, s[40:41]
	v_ashrrev_i32_e32 v1, 4, v18
	v_add_u32_e32 v20, 0x100, v18
	v_mad_i64_i32 v[4:5], s[40:41], v1, s92, v[2:3]
	v_ashrrev_i32_e32 v1, 4, v20
	v_add_u32_e32 v21, 0x200, v18
	v_mad_i64_i32 v[6:7], s[40:41], v1, s92, v[2:3]
	v_ashrrev_i32_e32 v1, 4, v21
	v_add_u32_e32 v22, 0x300, v18
	global_load_dwordx2 v[4:5], v[4:5], off
	v_mad_i64_i32 v[8:9], s[40:41], v1, s92, v[2:3]
	v_ashrrev_i32_e32 v1, 4, v22
	v_add_u32_e32 v23, 0x400, v18
	v_mad_i64_i32 v[10:11], s[40:41], v1, s92, v[2:3]
	v_ashrrev_i32_e32 v1, 4, v23
	v_mad_i64_i32 v[12:13], s[40:41], v1, s92, v[2:3]
	v_add_u32_e32 v24, 0x500, v18
	global_load_dwordx2 v[10:11], v[10:11], off
	v_ashrrev_i32_e32 v1, 4, v24
	global_load_dwordx2 v[12:13], v[12:13], off
	v_add_u32_e32 v25, 0x600, v18
	global_load_dwordx2 v[6:7], v[6:7], off
	v_mad_i64_i32 v[14:15], s[40:41], v1, s92, v[2:3]
	v_ashrrev_i32_e32 v1, 4, v25
	v_add_u32_e32 v26, 0x700, v18
	v_mad_i64_i32 v[16:17], s[40:41], v1, s92, v[2:3]
	v_ashrrev_i32_e32 v1, 4, v26
	global_load_dwordx2 v[14:15], v[14:15], off
	v_mad_i64_i32 v[2:3], s[40:41], v1, s92, v[2:3]
	s_or_b32 s40, s57, s47
	global_load_dwordx2 v[8:9], v[8:9], off
	s_ashr_i32 s41, s40, 31
	v_readlane_b32 s72, v253, 3
	global_load_dwordx2 v[16:17], v[16:17], off
	s_lshl_b64 s[40:41], s[40:41], 2
	v_readlane_b32 s80, v253, 11
	v_readlane_b32 s81, v253, 12
	s_add_u32 s40, s80, s40
	s_addc_u32 s41, s81, s41
	global_load_dwordx2 v[2:3], v[2:3], off
	v_mov_b32_e32 v27, s69
	global_load_dword v1, v201, s[40:41]
	v_ashrrev_i32_e32 v18, 3, v18
	s_movk_i32 s39, 0x110
	v_and_b32_e32 v18, -2, v18
	v_ashrrev_i32_e32 v20, 3, v20
	v_ashrrev_i32_e32 v21, 3, v21
	v_ashrrev_i32_e32 v22, 3, v22
	v_mad_u32_u24 v19, v19, s39, v27
	v_and_b32_e32 v20, -2, v20
	v_and_b32_e32 v21, -2, v21
	v_and_b32_e32 v22, -2, v22
	v_add_u32_e32 v18, v19, v18
	v_add_u32_e32 v20, v19, v20
	v_add_u32_e32 v21, v19, v21
	v_add_u32_e32 v22, v19, v22
	s_and_b64 vcc, exec, s[0:1]
	v_readlane_b32 s73, v253, 4
	v_readlane_b32 s74, v253, 5
	v_readlane_b32 s75, v253, 6
	v_readlane_b32 s76, v253, 7
	v_readlane_b32 s77, v253, 8
	v_readlane_b32 s78, v253, 9
	s_nop 3
	s_mov_b64 s[96:97], 0
	s_cbranch_vccnz .Lret_s0e_ptr
	s_lshl_b32 s98, s38, 4
	s_or_b32 s99, s48, s57
	s_add_i32 s98, s99, s98
	s_ashr_i32 s99, s98, 31
	s_lshl_b64 s[98:99], s[98:99], 14
	v_readlane_b32 s96, v254, 9
	v_readlane_b32 s97, v254, 10
	s_nop 3
	s_add_u32 s96, s96, s98
	s_addc_u32 s97, s97, s99
.Lret_s0e_ptr:
	v_mov_b32_e32 v110, 0
	v_mov_b32_e32 v111, 0
	v_mov_b32_e32 v112, 0
	v_mov_b32_e32 v113, 0
	v_mov_b32_e32 v114, 0
	v_mov_b32_e32 v115, 0
	v_mov_b32_e32 v116, 0
	v_mov_b32_e32 v117, 0
	v_mov_b32_e32 v118, 0
	v_mov_b32_e32 v119, 0
	v_mov_b32_e32 v120, 0
	v_mov_b32_e32 v121, 0
	v_mov_b32_e32 v122, 0
	v_mov_b32_e32 v123, 0
	v_mov_b32_e32 v124, 0
	v_mov_b32_e32 v125, 0
	s_cmp_lg_u64 s[96:97], 0
	s_cbranch_scc0 .Lret_s0e_skip
	v_mov_b32_e32 v126, v0
	v_mov_b32_e32 v127, 0
	s_mov_b64 s[98:99], 0x1000
	v_lshl_add_u64 v[126:127], v[126:127], 2, s[96:97]
	global_load_dword v110, v[126:127], off
	global_load_dword v111, v[126:127], off offset:1024
	global_load_dword v112, v[126:127], off offset:2048
	global_load_dword v113, v[126:127], off offset:3072
	v_lshl_add_u64 v[126:127], v[126:127], 0, s[98:99]
	global_load_dword v114, v[126:127], off
	global_load_dword v115, v[126:127], off offset:1024
	global_load_dword v116, v[126:127], off offset:2048
	global_load_dword v117, v[126:127], off offset:3072
	v_lshl_add_u64 v[126:127], v[126:127], 0, s[98:99]
	global_load_dword v118, v[126:127], off
	global_load_dword v119, v[126:127], off offset:1024
	global_load_dword v120, v[126:127], off offset:2048
	global_load_dword v121, v[126:127], off offset:3072
	v_lshl_add_u64 v[126:127], v[126:127], 0, s[98:99]
	global_load_dword v122, v[126:127], off
	global_load_dword v123, v[126:127], off offset:1024
	global_load_dword v124, v[126:127], off offset:2048
	global_load_dword v125, v[126:127], off offset:3072
.Lret_s0e_skip:
	s_waitcnt vmcnt(0)
	ds_write_b16 v18, v4 offset:36864
	ds_write_b16_d16_hi v18, v4 offset:37136
	ds_write_b16 v18, v5 offset:37408
	ds_write_b16_d16_hi v18, v5 offset:37680
	ds_write_b16 v20, v6 offset:36864
	ds_write_b16_d16_hi v20, v6 offset:37136
	ds_write_b16 v20, v7 offset:37408
	ds_write_b16_d16_hi v20, v7 offset:37680
	ds_write_b16 v21, v8 offset:36864
	ds_write_b16_d16_hi v21, v8 offset:37136
	ds_write_b16 v21, v9 offset:37408
	ds_write_b16_d16_hi v21, v9 offset:37680
	ds_write_b16 v22, v10 offset:36864
	ds_write_b16_d16_hi v22, v10 offset:37136
	ds_write_b16 v22, v11 offset:37408
	ds_write_b16_d16_hi v22, v11 offset:37680
	v_ashrrev_i32_e32 v4, 3, v23
	v_and_b32_e32 v4, -2, v4
	v_add_u32_e32 v4, v19, v4
	ds_write_b16 v4, v12 offset:36864
	ds_write_b16_d16_hi v4, v12 offset:37136
	ds_write_b16 v4, v13 offset:37408
	ds_write_b16_d16_hi v4, v13 offset:37680
	v_ashrrev_i32_e32 v4, 3, v24
	v_and_b32_e32 v4, -2, v4
	v_add_u32_e32 v4, v19, v4
	ds_write_b16 v4, v14 offset:36864
	ds_write_b16_d16_hi v4, v14 offset:37136
	ds_write_b16 v4, v15 offset:37408
	ds_write_b16_d16_hi v4, v15 offset:37680
	v_ashrrev_i32_e32 v4, 3, v25
	v_and_b32_e32 v4, -2, v4
	v_add_u32_e32 v4, v19, v4
	ds_write_b16 v4, v16 offset:36864
	ds_write_b16_d16_hi v4, v16 offset:37136
	ds_write_b16 v4, v17 offset:37408
	ds_write_b16_d16_hi v4, v17 offset:37680
	v_ashrrev_i32_e32 v4, 3, v26
	v_and_b32_e32 v4, -2, v4
	v_add_u32_e32 v4, v19, v4
	v_readlane_b32 s79, v253, 10
	v_readlane_b32 s82, v253, 13
	v_readlane_b32 s83, v253, 14
	v_readlane_b32 s84, v253, 15
	v_readlane_b32 s85, v253, 16
	v_readlane_b32 s86, v253, 17
	v_readlane_b32 s87, v253, 18
	ds_write_b16 v4, v2 offset:36864
	ds_write_b16_d16_hi v4, v2 offset:37136
	ds_write_b16 v4, v3 offset:37408
	ds_write_b16_d16_hi v4, v3 offset:37680
	s_cbranch_vccnz .LBB0_300
	s_lshl_b32 s38, s38, 4
	s_or_b32 s39, s48, s57
	s_add_i32 s38, s39, s38
	s_ashr_i32 s39, s38, 31
	v_readlane_b32 s72, v254, 5
	s_lshl_b64 s[38:39], s[38:39], 14
	v_readlane_b32 s76, v254, 9
	v_readlane_b32 s77, v254, 10
	s_add_u32 s40, s76, s38
	s_addc_u32 s41, s77, s39
	v_readlane_b32 s73, v254, 6
	v_readlane_b32 s74, v254, 7
	v_readlane_b32 s75, v254, 8
	v_readlane_b32 s78, v254, 11
	v_readlane_b32 s79, v254, 12
	v_readlane_b32 s80, v254, 13
	v_readlane_b32 s81, v254, 14
	v_readlane_b32 s82, v254, 15
	v_readlane_b32 s83, v254, 16
	v_readlane_b32 s84, v254, 17
	v_readlane_b32 s85, v254, 18
	v_readlane_b32 s86, v254, 19
	v_readlane_b32 s87, v254, 20
	s_branch .LBB0_301

.LBB0_301:
	v_mul_f32_e32 v2, 0xbfb8aa3b, v1
	v_rndne_f32_e32 v3, v2
	s_mov_b32 s38, 0xbfb8aa3b
	v_sub_f32_e32 v4, v2, v3
	v_fma_f32 v2, v1, s38, -v2
	v_fmac_f32_e32 v2, 0xb2a5705f, v1
	v_add_f32_e32 v2, v4, v2
	v_exp_f32_e32 v2, v2
	v_cvt_i32_f32_e32 v3, v3
	s_mov_b32 s38, 0x42ce8ed0
	v_cmp_nlt_f32_e32 vcc, s38, v1
	s_mov_b32 s38, 0xc2b17218
	v_ldexp_f32 v2, v2, v3
	v_cndmask_b32_e32 v2, 0, v2, vcc
	v_cmp_ngt_f32_e32 vcc, s38, v1
	s_mov_b32 s38, 0x3f2aaaab
	s_sub_i32 s56, s55, s29
	v_cndmask_b32_e32 v1, v252, v2, vcc
	v_add_f32_e32 v2, 1.0, v1
	v_add_f32_e32 v4, -1.0, v2
	v_sub_f32_e32 v5, v4, v2
	v_add_f32_e32 v5, 1.0, v5
	v_sub_f32_e32 v4, v1, v4
	v_add_f32_e32 v6, v4, v5
	v_frexp_mant_f32_e32 v7, v2
	v_cvt_f64_f32_e32 v[4:5], v2
	v_frexp_exp_i32_f64_e32 v4, v[4:5]
	v_cmp_gt_f32_e32 vcc, s38, v7
	s_mov_b32 s38, 0x3f317218
	s_ashr_i32 s58, s56, 7
	v_subbrev_co_u32_e32 v4, vcc, 0, v4, vcc
	v_sub_u32_e32 v5, 0, v4
	v_ldexp_f32 v2, v2, v5
	v_ldexp_f32 v5, v6, v5
	v_add_f32_e32 v6, -1.0, v2
	v_add_f32_e32 v9, 1.0, v2
	v_add_f32_e32 v7, 1.0, v6
	v_add_f32_e32 v10, -1.0, v9
	v_sub_f32_e32 v7, v2, v7
	v_sub_f32_e32 v2, v2, v10
	v_add_f32_e32 v2, v5, v2
	v_add_f32_e32 v7, v5, v7
	v_add_f32_e32 v5, v9, v2
	v_rcp_f32_e32 v10, v5
	v_add_f32_e32 v8, v6, v7
	v_sub_f32_e32 v6, v6, v8
	v_add_f32_e32 v6, v7, v6
	v_sub_f32_e32 v7, v9, v5
	v_add_f32_e32 v2, v2, v7
	v_mul_f32_e32 v7, v8, v10
	v_mul_f32_e32 v9, v5, v7
	v_fma_f32 v11, v7, v5, -v9
	v_fmac_f32_e32 v11, v7, v2
	v_add_f32_e32 v12, v9, v11
	v_sub_f32_e32 v13, v8, v12
	v_sub_f32_e32 v8, v8, v13
	v_sub_f32_e32 v9, v12, v9
	v_sub_f32_e32 v8, v8, v12
	v_add_f32_e32 v6, v6, v8
	v_sub_f32_e32 v8, v9, v11
	v_add_f32_e32 v6, v8, v6
	v_add_f32_e32 v8, v13, v6
	v_mul_f32_e32 v9, v10, v8
	v_mul_f32_e32 v11, v5, v9
	v_fma_f32 v5, v9, v5, -v11
	v_fmac_f32_e32 v5, v9, v2
	v_sub_f32_e32 v2, v13, v8
	v_add_f32_e32 v2, v6, v2
	v_add_f32_e32 v6, v11, v5
	v_sub_f32_e32 v12, v8, v6
	v_sub_f32_e32 v8, v8, v12
	v_sub_f32_e32 v11, v6, v11
	v_sub_f32_e32 v6, v8, v6
	v_add_f32_e32 v2, v2, v6
	v_sub_f32_e32 v5, v11, v5
	v_cvt_f32_i32_e32 v4, v4
	v_add_f32_e32 v2, v5, v2
	v_add_f32_e32 v5, v7, v9
	v_add_f32_e32 v2, v12, v2
	v_sub_f32_e32 v6, v5, v7
	v_mul_f32_e32 v2, v10, v2
	v_sub_f32_e32 v6, v9, v6
	v_add_f32_e32 v2, v6, v2
	v_mul_f32_e32 v9, 0x3f317218, v4
	v_add_f32_e32 v6, v5, v2
	v_fma_f32 v10, v4, s38, -v9
	v_mul_f32_e32 v7, v6, v6
	v_fmac_f32_e32 v10, 0xb102e308, v4
	v_sub_f32_e32 v4, v6, v5
	v_fmamk_f32 v8, v7, 0x3e9b6dac, v251
	v_sub_f32_e32 v2, v2, v4
	v_add_f32_e32 v4, v9, v10
	v_fmaak_f32 v8, v7, v8, 0x3f2aaada
	v_sub_f32_e32 v5, v4, v9
	v_ldexp_f32 v9, v6, 1
	v_mul_f32_e32 v6, v6, v7
	v_mul_f32_e32 v6, v6, v8
	v_add_f32_e32 v7, v9, v6
	v_sub_f32_e32 v8, v7, v9
	v_ldexp_f32 v2, v2, 1
	v_sub_f32_e32 v6, v6, v8
	v_add_f32_e32 v2, v2, v6
	v_add_f32_e32 v6, v7, v2
	v_sub_f32_e32 v7, v6, v7
	v_sub_f32_e32 v2, v2, v7
	v_add_f32_e32 v7, v4, v6
	v_sub_f32_e32 v8, v7, v4
	v_sub_f32_e32 v9, v7, v8
	v_sub_f32_e32 v5, v10, v5
	v_sub_f32_e32 v4, v4, v9
	v_sub_f32_e32 v6, v6, v8
	v_add_f32_e32 v4, v6, v4
	v_add_f32_e32 v6, v5, v2
	v_sub_f32_e32 v8, v6, v5
	v_sub_f32_e32 v9, v6, v8
	v_sub_f32_e32 v5, v5, v9
	v_sub_f32_e32 v2, v2, v8
	v_add_f32_e32 v4, v6, v4
	v_add_f32_e32 v2, v2, v5
	v_add_f32_e32 v5, v7, v4
	s_not_b32 s59, s58
	v_sub_f32_e32 v6, v5, v7
	s_mov_b32 s38, 0x7f800000
	s_add_i32 s42, s28, s59
	v_sub_f32_e32 v4, v4, v6
	v_cmp_neq_f32_e32 vcc, s38, v1
	s_and_b64 s[38:39], s[36:37], exec
	v_add_f32_e32 v2, v2, v4
	s_cselect_b32 s38, s58, s42
	v_add_f32_e32 v2, v5, v2
	v_cvt_f32_i32_e32 v4, s38
	s_mov_b32 s38, 0x33800000
	v_cndmask_b32_e32 v2, v252, v2, vcc
	v_cmp_lt_f32_e64 vcc, |v1|, s38
	s_cmp_lg_u64 s[40:41], 0
	s_cselect_b64 s[44:45], -1, 0
	v_cndmask_b32_e32 v76, v2, v1, vcc
	v_mul_f32_e32 v71, 0xc3000000, v76
	v_mul_f32_e32 v1, v71, v4
	v_mul_f32_e32 v1, 0x3fb8aa3b, v1
	v_exp_f32_e32 v18, v1
	s_and_b64 vcc, exec, s[44:45]
	v_ashrrev_i32_e32 v1, 31, v0
	s_mov_b32 s74, s91
	s_waitcnt vmcnt(0)
	v_mul_f32_e32 v2, v18, v110
	v_mul_f32_e32 v3, v18, v111
	v_mul_f32_e32 v4, v18, v112
	v_mul_f32_e32 v5, v18, v113
	v_mul_f32_e32 v6, v18, v114
	v_mul_f32_e32 v7, v18, v115
	v_mul_f32_e32 v8, v18, v116
	v_mul_f32_e32 v9, v18, v117
	v_mul_f32_e32 v10, v18, v118
	v_mul_f32_e32 v11, v18, v119
	v_mul_f32_e32 v12, v18, v120
	v_mul_f32_e32 v13, v18, v121
	v_mul_f32_e32 v14, v18, v122
	v_mul_f32_e32 v15, v18, v123
	v_mul_f32_e32 v16, v18, v124
	v_mul_f32_e32 v17, v18, v125
